# as v60 plus one compiler-convention wait state between a packed add and its consumer in the S5 tile
# speedup vs baseline: 1.0048x; 1.0048x over previous
.Ls5p_swap:
	v_permlane32_swap_b32_e32 v0, v112
	v_permlane32_swap_b32_e32 v1, v113
	v_permlane32_swap_b32_e32 v2, v114
	v_permlane32_swap_b32_e32 v3, v115
	v_permlane32_swap_b32_e32 v4, v116
	v_permlane32_swap_b32_e32 v5, v117
	v_permlane32_swap_b32_e32 v6, v118
	v_permlane32_swap_b32_e32 v7, v119
	v_permlane32_swap_b32_e32 v8, v120
	v_permlane32_swap_b32_e32 v9, v121
	v_permlane32_swap_b32_e32 v10, v122
	v_permlane32_swap_b32_e32 v11, v123
	v_permlane32_swap_b32_e32 v12, v124
	v_permlane32_swap_b32_e32 v13, v125
	v_permlane32_swap_b32_e32 v14, v126
	v_permlane32_swap_b32_e32 v15, v127
	v_permlane32_swap_b32_e32 v16, v160
	v_permlane32_swap_b32_e32 v17, v161
	v_permlane32_swap_b32_e32 v18, v162
	v_permlane32_swap_b32_e32 v19, v163
	v_permlane32_swap_b32_e32 v20, v164
	v_permlane32_swap_b32_e32 v21, v165
	v_permlane32_swap_b32_e32 v22, v166
	v_permlane32_swap_b32_e32 v23, v167
	v_permlane32_swap_b32_e32 v24, v168
	v_permlane32_swap_b32_e32 v25, v169
	v_permlane32_swap_b32_e32 v26, v170
	v_permlane32_swap_b32_e32 v27, v171
	v_permlane32_swap_b32_e32 v28, v172
	v_permlane32_swap_b32_e32 v29, v173
	v_permlane32_swap_b32_e32 v30, v174
	v_permlane32_swap_b32_e32 v31, v175
	v_fmac_f32_e32 v0, v80, v103
	v_fmac_f32_e32 v16, v80, v102
	v_fmac_f32_e32 v0, v89, v102
	v_fmac_f32_e32 v16, v81, v103
	v_fmac_f32_e32 v1, v80, v0
	v_fmac_f32_e32 v17, v80, v16
	v_cvt_pk_bf16_f32 v134, v0, v16
	v_fmac_f32_e32 v1, v89, v16
	v_fmac_f32_e32 v17, v81, v0
	v_fmac_f32_e32 v2, v80, v1
	v_fmac_f32_e32 v18, v80, v17
	v_cvt_pk_bf16_f32 v135, v1, v17
	v_fmac_f32_e32 v2, v89, v17
	v_fmac_f32_e32 v18, v81, v1
	ds_write_b32 v107, v134
	v_fmac_f32_e32 v3, v80, v2
	v_fmac_f32_e32 v19, v80, v18
	v_cvt_pk_bf16_f32 v136, v2, v18
	v_fmac_f32_e32 v3, v89, v18
	v_fmac_f32_e32 v19, v81, v2
	ds_write_b32 v107, v135 offset:528
	v_fmac_f32_e32 v112, v80, v3
	v_fmac_f32_e32 v160, v80, v19
	v_cvt_pk_bf16_f32 v137, v3, v19
	v_fmac_f32_e32 v112, v89, v19
	v_fmac_f32_e32 v160, v81, v3
	ds_write_b32 v107, v136 offset:1056
	v_fmac_f32_e32 v113, v80, v112
	v_fmac_f32_e32 v161, v80, v160
	v_cvt_pk_bf16_f32 v138, v112, v160
	v_fmac_f32_e32 v113, v89, v160
	v_fmac_f32_e32 v161, v81, v112
	ds_write_b32 v107, v137 offset:1584
	v_fmac_f32_e32 v114, v80, v113
	v_fmac_f32_e32 v162, v80, v161
	v_cvt_pk_bf16_f32 v139, v113, v161
	v_fmac_f32_e32 v114, v89, v161
	v_fmac_f32_e32 v162, v81, v113
	ds_write_b32 v107, v138 offset:2112
	v_fmac_f32_e32 v115, v80, v114
	v_fmac_f32_e32 v163, v80, v162
	v_cvt_pk_bf16_f32 v134, v114, v162
	v_fmac_f32_e32 v115, v89, v162
	v_fmac_f32_e32 v163, v81, v114
	ds_write_b32 v107, v139 offset:2640
	v_fmac_f32_e32 v4, v80, v115
	v_fmac_f32_e32 v20, v80, v163
	v_cvt_pk_bf16_f32 v135, v115, v163
	v_fmac_f32_e32 v4, v89, v163
	v_fmac_f32_e32 v20, v81, v115
	ds_write_b32 v107, v134 offset:3168
	v_fmac_f32_e32 v5, v80, v4
	v_fmac_f32_e32 v21, v80, v20
	v_cvt_pk_bf16_f32 v136, v4, v20
	v_fmac_f32_e32 v5, v89, v20
	v_fmac_f32_e32 v21, v81, v4
	ds_write_b32 v107, v135 offset:3696
	v_fmac_f32_e32 v6, v80, v5
	v_fmac_f32_e32 v22, v80, v21
	v_cvt_pk_bf16_f32 v137, v5, v21
	v_fmac_f32_e32 v6, v89, v21
	v_fmac_f32_e32 v22, v81, v5
	ds_write_b32 v107, v136 offset:4224
	v_fmac_f32_e32 v7, v80, v6
	v_fmac_f32_e32 v23, v80, v22
	v_cvt_pk_bf16_f32 v138, v6, v22
	v_fmac_f32_e32 v7, v89, v22
	v_fmac_f32_e32 v23, v81, v6
	ds_write_b32 v107, v137 offset:4752
	v_fmac_f32_e32 v116, v80, v7
	v_fmac_f32_e32 v164, v80, v23
	v_cvt_pk_bf16_f32 v139, v7, v23
	v_fmac_f32_e32 v116, v89, v23
	v_fmac_f32_e32 v164, v81, v7
	ds_write_b32 v107, v138 offset:5280
	v_fmac_f32_e32 v117, v80, v116
	v_fmac_f32_e32 v165, v80, v164
	v_cvt_pk_bf16_f32 v134, v116, v164
	v_fmac_f32_e32 v117, v89, v164
	v_fmac_f32_e32 v165, v81, v116
	ds_write_b32 v107, v139 offset:5808
	v_fmac_f32_e32 v118, v80, v117
	v_fmac_f32_e32 v166, v80, v165
	v_cvt_pk_bf16_f32 v135, v117, v165
	v_fmac_f32_e32 v118, v89, v165
	v_fmac_f32_e32 v166, v81, v117
	ds_write_b32 v107, v134 offset:6336
	v_fmac_f32_e32 v119, v80, v118
	v_fmac_f32_e32 v167, v80, v166
	v_cvt_pk_bf16_f32 v136, v118, v166
	v_fmac_f32_e32 v119, v89, v166
	v_fmac_f32_e32 v167, v81, v118
	ds_write_b32 v107, v135 offset:6864
	v_fmac_f32_e32 v8, v80, v119
	v_fmac_f32_e32 v24, v80, v167
	v_cvt_pk_bf16_f32 v137, v119, v167
	v_fmac_f32_e32 v8, v89, v167
	v_fmac_f32_e32 v24, v81, v119
	ds_write_b32 v107, v136 offset:7392
	v_fmac_f32_e32 v9, v80, v8
	v_fmac_f32_e32 v25, v80, v24
	v_cvt_pk_bf16_f32 v138, v8, v24
	v_fmac_f32_e32 v9, v89, v24
	v_fmac_f32_e32 v25, v81, v8
	ds_write_b32 v107, v137 offset:7920
	ds_read_b128 v[194:197], v108
	ds_read_b128 v[198:201], v108 offset:64
	ds_read_b128 v[202:205], v108 offset:128
	ds_read_b128 v[206:209], v108 offset:192
	v_fmac_f32_e32 v10, v80, v9
	v_fmac_f32_e32 v26, v80, v25
	v_cvt_pk_bf16_f32 v139, v9, v25
	v_fmac_f32_e32 v10, v89, v25
	v_fmac_f32_e32 v26, v81, v9
	ds_write_b32 v107, v138 offset:8448
	v_fmac_f32_e32 v11, v80, v10
	v_fmac_f32_e32 v27, v80, v26
	v_cvt_pk_bf16_f32 v134, v10, v26
	v_fmac_f32_e32 v11, v89, v26
	v_fmac_f32_e32 v27, v81, v10
	ds_write_b32 v107, v139 offset:8976
	v_fmac_f32_e32 v120, v80, v11
	v_fmac_f32_e32 v168, v80, v27
	v_cvt_pk_bf16_f32 v135, v11, v27
	v_fmac_f32_e32 v120, v89, v27
	v_fmac_f32_e32 v168, v81, v11
	ds_write_b32 v107, v134 offset:9504
	v_fmac_f32_e32 v121, v80, v120
	v_fmac_f32_e32 v169, v80, v168
	v_cvt_pk_bf16_f32 v136, v120, v168
	v_fmac_f32_e32 v121, v89, v168
	v_fmac_f32_e32 v169, v81, v120
	ds_write_b32 v107, v135 offset:10032
	v_fmac_f32_e32 v122, v80, v121
	v_fmac_f32_e32 v170, v80, v169
	v_cvt_pk_bf16_f32 v137, v121, v169
	v_fmac_f32_e32 v122, v89, v169
	v_fmac_f32_e32 v170, v81, v121
	ds_write_b32 v107, v136 offset:10560
	s_waitcnt lgkmcnt(5)
	v_mfma_f32_16x16x32_bf16 v[226:229], v[48:51], v[194:197], 0
	v_fmac_f32_e32 v123, v80, v122
	v_fmac_f32_e32 v171, v80, v170
	v_cvt_pk_bf16_f32 v138, v122, v170
	v_fmac_f32_e32 v123, v89, v170
	v_fmac_f32_e32 v171, v81, v122
	ds_write_b32 v107, v137 offset:11088
	v_mfma_f32_16x16x32_bf16 v[226:229], v[52:55], v[198:201], v[226:229]
	v_fmac_f32_e32 v12, v80, v123
	v_fmac_f32_e32 v28, v80, v171
	v_cvt_pk_bf16_f32 v139, v123, v171
	v_fmac_f32_e32 v12, v89, v171
	v_fmac_f32_e32 v28, v81, v123
	ds_write_b32 v107, v138 offset:11616
	v_mfma_f32_16x16x32_bf16 v[226:229], v[56:59], v[202:205], v[226:229]
	v_fmac_f32_e32 v13, v80, v12
	v_fmac_f32_e32 v29, v80, v28
	v_cvt_pk_bf16_f32 v134, v12, v28
	v_fmac_f32_e32 v13, v89, v28
	v_fmac_f32_e32 v29, v81, v12
	ds_write_b32 v107, v139 offset:12144
	v_mfma_f32_16x16x32_bf16 v[226:229], v[60:63], v[206:209], v[226:229]
	v_fmac_f32_e32 v14, v80, v13
	v_fmac_f32_e32 v30, v80, v29
	v_cvt_pk_bf16_f32 v135, v13, v29
	v_fmac_f32_e32 v14, v89, v29
	v_fmac_f32_e32 v30, v81, v13
	ds_write_b32 v107, v134 offset:12672
	v_fmac_f32_e32 v15, v80, v14
	v_fmac_f32_e32 v31, v80, v30
	v_cvt_pk_bf16_f32 v136, v14, v30
	v_fmac_f32_e32 v15, v89, v30
	v_fmac_f32_e32 v31, v81, v14
	ds_write_b32 v107, v135 offset:13200
	v_fmac_f32_e32 v124, v80, v15
	v_fmac_f32_e32 v172, v80, v31
	v_cvt_pk_bf16_f32 v137, v15, v31
	v_fmac_f32_e32 v124, v89, v31
	v_fmac_f32_e32 v172, v81, v15
	ds_write_b32 v107, v136 offset:13728
	v_fmac_f32_e32 v125, v80, v124
	v_fmac_f32_e32 v173, v80, v172
	v_cvt_pk_bf16_f32 v138, v124, v172
	v_fmac_f32_e32 v125, v89, v172
	v_fmac_f32_e32 v173, v81, v124
	ds_write_b32 v107, v137 offset:14256
	v_fmac_f32_e32 v126, v80, v125
	v_fmac_f32_e32 v174, v80, v173
	v_cvt_pk_bf16_f32 v139, v125, v173
	v_fmac_f32_e32 v126, v89, v173
	v_fmac_f32_e32 v174, v81, v125
	ds_write_b32 v107, v138 offset:14784
	v_fma_f32 v103, v80, v126, v127
	v_fma_f32 v102, v80, v174, v175
	v_cvt_pk_bf16_f32 v134, v126, v174
	v_fmac_f32_e32 v103, v89, v174
	v_fmac_f32_e32 v102, v81, v126
	ds_write_b32 v107, v139 offset:15312
	v_cvt_pk_bf16_f32 v135, v103, v102
	ds_write_b32 v107, v134 offset:15840
	ds_write_b32 v107, v135 offset:16368
	v_mov_b64_e32 v[18:19], s[16:17]
	ds_read_b128 v[194:197], v108 offset:8448
	ds_read_b128 v[198:201], v108 offset:8512
	ds_read_b128 v[202:205], v108 offset:8576
	ds_read_b128 v[206:209], v108 offset:8640
	v_lshlrev_b32_e32 v10, 16, v100
	v_and_b32_e32 v11, 0xffff0000, v100
	v_pk_fma_f32 v[14:15], v[64:65], v[10:11], v[226:227]
	s_nop 0
	v_pk_mul_f32 v[6:7], v[14:15], v[14:15]
	s_nop 0
	v_pk_fma_f32 v[6:7], v[6:7], s[10:11], v[18:19] op_sel_hi:[1,0,0] neg_lo:[1,0,0] neg_hi:[1,0,0]
	s_nop 0
	v_pk_mul_f32 v[6:7], v[14:15], v[6:7]
	s_nop 0
	v_exp_f32_e32 v6, v6
	v_exp_f32_e32 v7, v7
	s_nop 0
	v_pk_add_f32 v[10:11], v[6:7], 1.0 op_sel_hi:[1,0]
	v_lshlrev_b32_e32 v6, 16, v101
	v_and_b32_e32 v7, 0xffff0000, v101
	v_pk_fma_f32 v[20:21], v[66:67], v[6:7], v[228:229]
	v_rcp_f32_e32 v16, v10
	v_pk_mul_f32 v[6:7], v[20:21], v[20:21]
	v_rcp_f32_e32 v17, v11
	v_pk_fma_f32 v[6:7], v[6:7], s[10:11], v[18:19] op_sel_hi:[1,0,0] neg_lo:[1,0,0] neg_hi:[1,0,0]
	s_nop 0
	s_nop 0
	v_pk_mul_f32 v[6:7], v[20:21], v[6:7]
	v_pk_mul_f32 v[24:25], v[14:15], v[16:17]
	v_exp_f32_e32 v12, v6
	v_exp_f32_e32 v13, v7
	s_nop 0
	v_pk_add_f32 v[22:23], v[12:13], 1.0 op_sel_hi:[1,0]
	s_waitcnt lgkmcnt(3)
	v_mfma_f32_16x16x32_bf16 v[6:9], v[48:51], v[194:197], 0
	v_rcp_f32_e32 v22, v22
	v_rcp_f32_e32 v23, v23
	s_waitcnt lgkmcnt(2)
	v_mfma_f32_16x16x32_bf16 v[6:9], v[52:55], v[198:201], v[6:9]
	v_pk_mul_f32 v[20:21], v[20:21], v[22:23]
	v_cvt_pk_bf16_f32 v22, v24, v25
	s_waitcnt lgkmcnt(1)
	v_mfma_f32_16x16x32_bf16 v[6:9], v[56:59], v[202:205], v[6:9]
	s_waitcnt lgkmcnt(0)
	v_mfma_f32_16x16x32_bf16 v[6:9], v[60:63], v[206:209], v[6:9]
	v_lshlrev_b32_e32 v10, 16, v94
	v_and_b32_e32 v11, 0xffff0000, v94
	v_lshlrev_b32_e32 v12, 16, v95
	v_and_b32_e32 v13, 0xffff0000, v95
	s_nop 3
	v_pk_fma_f32 v[6:7], v[64:65], v[10:11], v[6:7]
	v_pk_fma_f32 v[8:9], v[66:67], v[12:13], v[8:9]
	v_pk_mul_f32 v[10:11], v[6:7], v[6:7]
	v_pk_mul_f32 v[12:13], v[8:9], v[8:9]
	v_pk_fma_f32 v[10:11], v[10:11], s[10:11], v[18:19] op_sel_hi:[1,0,0] neg_lo:[1,0,0] neg_hi:[1,0,0]
	v_pk_fma_f32 v[12:13], v[12:13], s[10:11], v[18:19] op_sel_hi:[1,0,0] neg_lo:[1,0,0] neg_hi:[1,0,0]
	v_pk_mul_f32 v[10:11], v[6:7], v[10:11]
	v_pk_mul_f32 v[12:13], v[8:9], v[12:13]
	v_exp_f32_e32 v10, v10
	v_exp_f32_e32 v11, v11
	v_exp_f32_e32 v12, v12
	v_exp_f32_e32 v13, v13
	v_pk_add_f32 v[10:11], v[10:11], 1.0 op_sel_hi:[1,0]
	s_nop 0
	v_rcp_f32_e32 v10, v10
	v_rcp_f32_e32 v11, v11
	v_pk_add_f32 v[12:13], v[12:13], 1.0 op_sel_hi:[1,0]
	v_cvt_pk_bf16_f32 v23, v20, v21
	global_store_dwordx2 v[236:237], v[22:23], off
	v_rcp_f32_e32 v12, v12
	v_rcp_f32_e32 v13, v13
	v_pk_mul_f32 v[6:7], v[6:7], v[10:11]
	s_nop 0
	s_nop 0
	v_cvt_pk_bf16_f32 v6, v6, v7
	v_pk_mul_f32 v[8:9], v[8:9], v[12:13]
	s_nop 0
	v_cvt_pk_bf16_f32 v7, v8, v9
	global_store_dwordx2 v[238:239], v[6:7], off
	v_lshl_add_u64 v[236:237], v[236:237], 0, s[50:51]
	v_lshl_add_u64 v[238:239], v[238:239], 0, s[50:51]
	s_add_i32 s5, s5, 32
	s_add_i32 s6, s6, 1
	s_waitcnt vmcnt(2)
	v_mov_b64_e32 v[100:101], v[190:191]
	v_mov_b64_e32 v[94:95], v[192:193]
	s_cmp_lt_u32 s6, 64
	s_cbranch_scc1 .Ls5p_tile
	s_branch .LBB0_463
